# v20lanedefer
# speedup vs baseline: 1.0023x; 1.0020x over previous
; #define SBAR() __builtin_amdgcn_sched_barrier(0)
; #define PV_RD(F_, d0) do { constexpr int b_ = V_OFF + v_rd_off(d0, 0, 0); \
;         TRRD(F_[0], b_); TRRD(F_[1], b_ + 2048); TRRD(F_[2], b_ + 4096); TRRD(F_[3], b_ + 6144); TRRD(F_[4], b_ + 8192); TRRD(F_[5], b_ + 10240); TRRD(F_[6], b_ + 12288); TRRD(F_[7], b_ + 14336); } while (0)
; template <int k> __device__ __forceinline__ void par_snip(f32x16& p0, f32x16& p1, float& m_reg, float& pmax, float& alpha, float& mnL, float msk) {
;     constexpr float C2 = 1.4426950408889634f * SCALE;
;     if constexpr (k < 4) { constexpr int j = 4 * k; const float a = fmaxf(fmaxf(p0[j], p0[j + 1]), fmaxf(p0[j + 2], p0[j + 3])), b = fmaxf(fmaxf(p1[j], p1[j + 1]), fmaxf(p1[j + 2], p1[j + 3]));
;         pmax = (k == 0) ? fmaxf(a, b) : fmaxf(pmax, fmaxf(a, b)); }
;     else if constexpr (k == 4) { pmax += msk;
;         { auto rr = __builtin_amdgcn_permlane32_swap(__float_as_uint(pmax), __float_as_uint(pmax), false, false); pmax = fmaxf(__uint_as_float(rr[0]), __uint_as_float(rr[1])); }
;         const bool defer = __all((pmax - m_reg) * SCALE <= THR);
;         const float mn = defer ? m_reg : fmaxf(m_reg, pmax);
;         alpha = __builtin_amdgcn_exp2f((m_reg - mn) * C2); m_reg = mn; mnL = fmaf(-mn, C2, msk); }
;     else if constexpr (k < 9) { constexpr int j = 4 * (k - 5);
; #pragma unroll
;         for (int e = 0; e < 4; ++e) { p0[j + e] = fmaf(p0[j + e], C2, mnL); p1[j + e] = fmaf(p1[j + e], C2, mnL); } }
;     else if constexpr (k < 15) { constexpr int j = 2 * (k - 9); p0[j] = __builtin_amdgcn_exp2f(p0[j]); p0[j + 1] = __builtin_amdgcn_exp2f(p0[j + 1]); }
;     else if constexpr (k == 15) {
; #pragma unroll
;         for (int e = 12; e < 16; ++e) p0[e] = __builtin_amdgcn_exp2f(p0[e]); }
; }
; __device__ __forceinline__ void stage_pv_par(f32x16* o, int vb0, bf16x8 pa0, bf16x8 pa1, bf16x8 pa2, bf16x8 pa3,
;                                              f32x16& x0, f32x16& x1, float& m_reg, float& alpha, float msk) {
;     ...
;     float pmax = 0.f, mnL = 0.f; s16x4 fA[8];
;     SBAR(); PV_RD(fA, 0); PV_WAIT(fA, 0); SBAR();
;     PVS(fA, 0); PV_RD(fA, 1); PV_WAIT(fA, 0); SBAR();
;     PVS(fA, 1); PV_RD(fA, 2); PV_WAIT(fA, 0); SBAR();
;     PVS(fA, 2); PV_RD(fA, 3); PV_WAIT(fA, 0); SBAR();
;     PVS(fA, 3);
.Lmy_mid_a:
	s_and_b32 s34, s85, 0xc000
	v_add_u32_e32 v217, s34, v225
	ds_read_b64_tr_b16 v[194:195], v217 offset:0
	ds_read_b64_tr_b16 v[196:197], v217 offset:0x800
	ds_read_b64_tr_b16 v[200:201], v217 offset:0x1000
	ds_read_b64_tr_b16 v[202:203], v217 offset:0x1800
	ds_read_b64_tr_b16 v[204:205], v217 offset:0x2000
	ds_read_b64_tr_b16 v[206:207], v217 offset:0x2800
	ds_read_b64_tr_b16 v[208:209], v217 offset:0x3000
	ds_read_b64_tr_b16 v[210:211], v217 offset:0x3800
	s_nop 0
	s_waitcnt lgkmcnt(0)
	s_nop 0
	v_mfma_f32_32x32x16_bf16 v[64:79], v[194:197], v[2:5], v[64:79]
	s_nop 5
	v_max3_f32 v0, v96, v97, v98
	v_max3_f32 v194, v112, v113, v114
	v_max3_f32 v0, v0, v99, v100
	v_max3_f32 v194, v194, v115, v116
	v_mfma_f32_32x32x16_bf16 v[64:79], v[200:203], v[6:9], v[64:79]
	v_max3_f32 v0, v0, v101, v102
	v_max3_f32 v194, v194, v117, v118
	v_max3_f32 v0, v0, v103, v104
	v_max3_f32 v194, v194, v119, v120
	v_mfma_f32_32x32x16_bf16 v[64:79], v[204:207], v[10:13], v[64:79]
	v_max3_f32 v0, v0, v105, v106
	v_max3_f32 v194, v194, v121, v122
	v_max3_f32 v0, v0, v107, v108
	v_max3_f32 v194, v194, v123, v124
	v_mfma_f32_32x32x16_bf16 v[64:79], v[208:211], v[176:179], v[64:79]
	v_max3_f32 v0, v0, v109, v110
	v_max3_f32 v194, v194, v125, v126
	v_max3_f32 v0, v0, v111, v127
	v_max_f32_e32 v0, v0, v194
	ds_read_b64_tr_b16 v[194:195], v217 offset:0x200
	ds_read_b64_tr_b16 v[196:197], v217 offset:0xa00
	ds_read_b64_tr_b16 v[200:201], v217 offset:0x1200
	ds_read_b64_tr_b16 v[202:203], v217 offset:0x1a00
	ds_read_b64_tr_b16 v[204:205], v217 offset:0x2200
	ds_read_b64_tr_b16 v[206:207], v217 offset:0x2a00
	ds_read_b64_tr_b16 v[208:209], v217 offset:0x3200
	ds_read_b64_tr_b16 v[210:211], v217 offset:0x3a00
	s_nop 0
	s_waitcnt lgkmcnt(0)
	v_add_f32_e32 v0, v216, v0
	v_mfma_f32_32x32x16_bf16 v[48:63], v[194:197], v[2:5], v[48:63]
	v_mov_b32_e32 v194, v0
	s_nop 1
	v_permlane32_swap_b32_e32 v0, v194
	v_max_f32_e32 v0, v0, v194
	v_sub_f32_e32 v194, v0, v244
	v_mul_f32_e32 v194, 0x3d93cd3a, v194
	v_cmp_ge_f32_e32 vcc, s63, v194
	v_max_f32_e32 v0, v244, v0
	s_nop 0
	v_cndmask_b32_e32 v246, v0, v244, vcc
	v_sub_f32_e32 v0, v244, v246
	v_mul_f32_e32 v0, 0x3dd53b94, v0
	v_exp_f32_e32 v0, v0
	v_fmac_f32_e32 v216, 0xbdd53b94, v246
	v_mfma_f32_32x32x16_bf16 v[48:63], v[200:203], v[6:9], v[48:63]
	v_fmamk_f32 v96, v96, 0x3dd53b94, v216
	v_fmamk_f32 v97, v97, 0x3dd53b94, v216
	v_fmamk_f32 v98, v98, 0x3dd53b94, v216
	v_fmamk_f32 v99, v99, 0x3dd53b94, v216
	v_exp_f32_e32 v243, v96
	v_mfma_f32_32x32x16_bf16 v[48:63], v[204:207], v[10:13], v[48:63]
	v_fmamk_f32 v100, v100, 0x3dd53b94, v216
	v_fmamk_f32 v101, v101, 0x3dd53b94, v216
	v_exp_f32_e32 v242, v97
	v_exp_f32_e32 v241, v98
	v_mfma_f32_32x32x16_bf16 v[48:63], v[208:211], v[176:179], v[48:63]
	v_fmamk_f32 v102, v102, 0x3dd53b94, v216
	v_fmamk_f32 v103, v103, 0x3dd53b94, v216
	v_exp_f32_e32 v240, v99
	v_exp_f32_e32 v239, v100
	ds_read_b64_tr_b16 v[194:195], v217 offset:0x400
	ds_read_b64_tr_b16 v[196:197], v217 offset:0xc00
	ds_read_b64_tr_b16 v[200:201], v217 offset:0x1400
	ds_read_b64_tr_b16 v[202:203], v217 offset:0x1c00
	ds_read_b64_tr_b16 v[204:205], v217 offset:0x2400
	ds_read_b64_tr_b16 v[206:207], v217 offset:0x2c00
	ds_read_b64_tr_b16 v[208:209], v217 offset:0x3400
	ds_read_b64_tr_b16 v[210:211], v217 offset:0x3c00
	s_nop 0
	s_waitcnt lgkmcnt(0)
	s_nop 0
	v_mfma_f32_32x32x16_bf16 v[32:47], v[194:197], v[2:5], v[32:47]
	v_fmamk_f32 v104, v104, 0x3dd53b94, v216
	v_fmamk_f32 v105, v105, 0x3dd53b94, v216
	v_exp_f32_e32 v238, v101
	v_exp_f32_e32 v237, v102
	v_mfma_f32_32x32x16_bf16 v[32:47], v[200:203], v[6:9], v[32:47]
	v_fmamk_f32 v106, v106, 0x3dd53b94, v216
	v_fmamk_f32 v107, v107, 0x3dd53b94, v216
	v_exp_f32_e32 v236, v103
	v_exp_f32_e32 v235, v104
	v_mfma_f32_32x32x16_bf16 v[32:47], v[204:207], v[10:13], v[32:47]
	v_fmamk_f32 v108, v108, 0x3dd53b94, v216
	v_fmamk_f32 v109, v109, 0x3dd53b94, v216
	v_exp_f32_e32 v234, v105
	v_exp_f32_e32 v233, v106
	v_mfma_f32_32x32x16_bf16 v[32:47], v[208:211], v[176:179], v[32:47]
	v_fmamk_f32 v110, v110, 0x3dd53b94, v216
	v_fmamk_f32 v111, v111, 0x3dd53b94, v216
	v_exp_f32_e32 v232, v107
	v_exp_f32_e32 v231, v108
	ds_read_b64_tr_b16 v[194:195], v217 offset:0x600
	ds_read_b64_tr_b16 v[196:197], v217 offset:0xe00
	ds_read_b64_tr_b16 v[200:201], v217 offset:0x1600
	ds_read_b64_tr_b16 v[202:203], v217 offset:0x1e00
	ds_read_b64_tr_b16 v[204:205], v217 offset:0x2600
	ds_read_b64_tr_b16 v[206:207], v217 offset:0x2e00
	ds_read_b64_tr_b16 v[208:209], v217 offset:0x3600
	ds_read_b64_tr_b16 v[210:211], v217 offset:0x3e00
	s_nop 0
	s_waitcnt lgkmcnt(0)
	s_nop 0
	v_mfma_f32_32x32x16_bf16 v[16:31], v[194:197], v[2:5], v[16:31]
	v_exp_f32_e32 v230, v109
	v_fmamk_f32 v14, v112, 0x3dd53b94, v216
	v_fmamk_f32 v15, v113, 0x3dd53b94, v216
	v_fmamk_f32 v116, v116, 0x3dd53b94, v216
	v_fmamk_f32 v117, v117, 0x3dd53b94, v216
	v_mfma_f32_32x32x16_bf16 v[16:31], v[200:203], v[6:9], v[16:31]
	v_fmamk_f32 v118, v118, 0x3dd53b94, v216
	v_fmamk_f32 v119, v119, 0x3dd53b94, v216
	v_fmamk_f32 v120, v120, 0x3dd53b94, v216
	v_fmamk_f32 v121, v121, 0x3dd53b94, v216
	v_fmamk_f32 v122, v122, 0x3dd53b94, v216
	v_fmamk_f32 v123, v123, 0x3dd53b94, v216
	v_mfma_f32_32x32x16_bf16 v[16:31], v[204:207], v[10:13], v[16:31]
	v_fmamk_f32 v124, v124, 0x3dd53b94, v216
	v_fmamk_f32 v125, v125, 0x3dd53b94, v216
	v_fmamk_f32 v126, v126, 0x3dd53b94, v216
	v_fmamk_f32 v127, v127, 0x3dd53b94, v216
	v_mfma_f32_32x32x16_bf16 v[16:31], v[208:211], v[176:179], v[16:31]
	v_cmp_gt_f32_e32 vcc, 1.0, v0
	s_cbranch_vccz .LBB0_330
	v_pk_mul_f32 v[78:79], v[78:79], v[0:1] op_sel_hi:[1,0]
	v_pk_mul_f32 v[76:77], v[76:77], v[0:1] op_sel_hi:[1,0]
	v_pk_mul_f32 v[74:75], v[74:75], v[0:1] op_sel_hi:[1,0]
	v_pk_mul_f32 v[72:73], v[72:73], v[0:1] op_sel_hi:[1,0]
	v_pk_mul_f32 v[70:71], v[70:71], v[0:1] op_sel_hi:[1,0]
	v_pk_mul_f32 v[68:69], v[68:69], v[0:1] op_sel_hi:[1,0]
	v_pk_mul_f32 v[66:67], v[66:67], v[0:1] op_sel_hi:[1,0]
	v_pk_mul_f32 v[64:65], v[64:65], v[0:1] op_sel_hi:[1,0]
	v_pk_mul_f32 v[62:63], v[0:1], v[62:63] op_sel_hi:[0,1]
	v_pk_mul_f32 v[60:61], v[0:1], v[60:61] op_sel_hi:[0,1]
	v_pk_mul_f32 v[58:59], v[0:1], v[58:59] op_sel_hi:[0,1]
	v_pk_mul_f32 v[56:57], v[0:1], v[56:57] op_sel_hi:[0,1]
	v_pk_mul_f32 v[54:55], v[0:1], v[54:55] op_sel_hi:[0,1]
	v_pk_mul_f32 v[52:53], v[0:1], v[52:53] op_sel_hi:[0,1]
	v_pk_mul_f32 v[50:51], v[0:1], v[50:51] op_sel_hi:[0,1]
	v_pk_mul_f32 v[48:49], v[0:1], v[48:49] op_sel_hi:[0,1]
	v_pk_mul_f32 v[46:47], v[0:1], v[46:47] op_sel_hi:[0,1]
	v_pk_mul_f32 v[44:45], v[0:1], v[44:45] op_sel_hi:[0,1]
	v_pk_mul_f32 v[42:43], v[0:1], v[42:43] op_sel_hi:[0,1]
	v_pk_mul_f32 v[40:41], v[0:1], v[40:41] op_sel_hi:[0,1]
	v_pk_mul_f32 v[38:39], v[0:1], v[38:39] op_sel_hi:[0,1]
	v_pk_mul_f32 v[36:37], v[0:1], v[36:37] op_sel_hi:[0,1]
	v_pk_mul_f32 v[34:35], v[0:1], v[34:35] op_sel_hi:[0,1]
	v_pk_mul_f32 v[32:33], v[0:1], v[32:33] op_sel_hi:[0,1]
	v_pk_mul_f32 v[30:31], v[0:1], v[30:31] op_sel_hi:[0,1]
	v_pk_mul_f32 v[28:29], v[0:1], v[28:29] op_sel_hi:[0,1]
	v_pk_mul_f32 v[26:27], v[0:1], v[26:27] op_sel_hi:[0,1]
	v_pk_mul_f32 v[24:25], v[0:1], v[24:25] op_sel_hi:[0,1]
	v_pk_mul_f32 v[22:23], v[0:1], v[22:23] op_sel_hi:[0,1]
	v_pk_mul_f32 v[20:21], v[0:1], v[20:21] op_sel_hi:[0,1]
	v_pk_mul_f32 v[18:19], v[0:1], v[18:19] op_sel_hi:[0,1]
	v_pk_mul_f32 v[16:17], v[0:1], v[16:17] op_sel_hi:[0,1]

; #define SBAR() __builtin_amdgcn_sched_barrier(0)
; #define PV_RD(F_, d0) do { constexpr int b_ = V_OFF + v_rd_off(d0, 0, 0); \
;         TRRD(F_[0], b_); TRRD(F_[1], b_ + 2048); TRRD(F_[2], b_ + 4096); TRRD(F_[3], b_ + 6144); TRRD(F_[4], b_ + 8192); TRRD(F_[5], b_ + 10240); TRRD(F_[6], b_ + 12288); TRRD(F_[7], b_ + 14336); } while (0)
; template <int k> __device__ __forceinline__ void par_snip(f32x16& p0, f32x16& p1, float& m_reg, float& pmax, float& alpha, float& mnL, float msk) {
;     constexpr float C2 = 1.4426950408889634f * SCALE;
;     if constexpr (k < 4) { constexpr int j = 4 * k; const float a = fmaxf(fmaxf(p0[j], p0[j + 1]), fmaxf(p0[j + 2], p0[j + 3])), b = fmaxf(fmaxf(p1[j], p1[j + 1]), fmaxf(p1[j + 2], p1[j + 3]));
;         pmax = (k == 0) ? fmaxf(a, b) : fmaxf(pmax, fmaxf(a, b)); }
;     else if constexpr (k == 4) { pmax += msk;
;         { auto rr = __builtin_amdgcn_permlane32_swap(__float_as_uint(pmax), __float_as_uint(pmax), false, false); pmax = fmaxf(__uint_as_float(rr[0]), __uint_as_float(rr[1])); }
;         const bool defer = __all((pmax - m_reg) * SCALE <= THR);
;         const float mn = defer ? m_reg : fmaxf(m_reg, pmax);
;         alpha = __builtin_amdgcn_exp2f((m_reg - mn) * C2); m_reg = mn; mnL = fmaf(-mn, C2, msk); }
;     else if constexpr (k < 9) { constexpr int j = 4 * (k - 5);
; #pragma unroll
;         for (int e = 0; e < 4; ++e) { p0[j + e] = fmaf(p0[j + e], C2, mnL); p1[j + e] = fmaf(p1[j + e], C2, mnL); } }
;     else if constexpr (k < 15) { constexpr int j = 2 * (k - 9); p0[j] = __builtin_amdgcn_exp2f(p0[j]); p0[j + 1] = __builtin_amdgcn_exp2f(p0[j + 1]); }
;     else if constexpr (k == 15) {
; #pragma unroll
;         for (int e = 12; e < 16; ++e) p0[e] = __builtin_amdgcn_exp2f(p0[e]); }
; }
; __device__ __forceinline__ void stage_pv_par(f32x16* o, int vb0, bf16x8 pa0, bf16x8 pa1, bf16x8 pa2, bf16x8 pa3,
;                                              f32x16& x0, f32x16& x1, float& m_reg, float& alpha, float msk) {
;     ...
;     float pmax = 0.f, mnL = 0.f; s16x4 fA[8];
;     SBAR(); PV_RD(fA, 0); PV_WAIT(fA, 0); SBAR();
;     PVS(fA, 0); PV_RD(fA, 1); PV_WAIT(fA, 0); SBAR();
;     PVS(fA, 1); PV_RD(fA, 2); PV_WAIT(fA, 0); SBAR();
;     PVS(fA, 2); PV_RD(fA, 3); PV_WAIT(fA, 0); SBAR();
;     PVS(fA, 3);
.Lmy_mid_b:
	s_and_b32 s34, s34, 0xc000
	v_add_u32_e32 v217, s34, v225
	ds_read_b64_tr_b16 v[194:195], v217 offset:0
	ds_read_b64_tr_b16 v[196:197], v217 offset:0x800
	ds_read_b64_tr_b16 v[232:233], v217 offset:0x1000
	ds_read_b64_tr_b16 v[234:235], v217 offset:0x1800
	ds_read_b64_tr_b16 v[236:237], v217 offset:0x2000
	ds_read_b64_tr_b16 v[238:239], v217 offset:0x2800
	ds_read_b64_tr_b16 v[240:241], v217 offset:0x3000
	ds_read_b64_tr_b16 v[242:243], v217 offset:0x3800
	s_nop 0
	s_waitcnt lgkmcnt(0)
	s_nop 0
	v_mfma_f32_32x32x16_bf16 v[64:79], v[194:197], v[2:5], v[64:79]
	s_nop 5
	v_max3_f32 v192, v96, v97, v98
	v_max3_f32 v194, v80, v81, v82
	v_max3_f32 v192, v192, v99, v100
	v_max3_f32 v194, v194, v83, v84
	v_mfma_f32_32x32x16_bf16 v[64:79], v[232:235], v[6:9], v[64:79]
	v_max3_f32 v192, v192, v101, v102
	v_max3_f32 v194, v194, v85, v86
	v_max3_f32 v192, v192, v103, v104
	v_max3_f32 v194, v194, v87, v88
	v_mfma_f32_32x32x16_bf16 v[64:79], v[236:239], v[10:13], v[64:79]
	v_max3_f32 v192, v192, v105, v106
	v_max3_f32 v194, v194, v89, v90
	v_max3_f32 v192, v192, v107, v108
	v_max3_f32 v194, v194, v91, v92
	v_mfma_f32_32x32x16_bf16 v[64:79], v[240:243], v[112:115], v[64:79]
	v_max3_f32 v192, v192, v109, v110
	v_max3_f32 v194, v194, v93, v94
	v_max3_f32 v192, v192, v111, v95
	v_max_f32_e32 v192, v192, v194
	ds_read_b64_tr_b16 v[194:195], v217 offset:0x200
	ds_read_b64_tr_b16 v[196:197], v217 offset:0xa00
	ds_read_b64_tr_b16 v[232:233], v217 offset:0x1200
	ds_read_b64_tr_b16 v[234:235], v217 offset:0x1a00
	ds_read_b64_tr_b16 v[236:237], v217 offset:0x2200
	ds_read_b64_tr_b16 v[238:239], v217 offset:0x2a00
	ds_read_b64_tr_b16 v[240:241], v217 offset:0x3200
	ds_read_b64_tr_b16 v[242:243], v217 offset:0x3a00
	s_nop 0
	s_waitcnt lgkmcnt(0)
	v_add_f32_e32 v192, v178, v192
	v_mfma_f32_32x32x16_bf16 v[48:63], v[194:197], v[2:5], v[48:63]
	v_mov_b32_e32 v194, v192
	s_nop 1
	v_permlane32_swap_b32_e32 v192, v194
	v_max_f32_e32 v192, v192, v194
	v_sub_f32_e32 v194, v192, v246
	v_mul_f32_e32 v194, 0x3d93cd3a, v194
	v_cmp_ge_f32_e32 vcc, s63, v194
	v_max_f32_e32 v192, v246, v192
	s_nop 0
	v_cndmask_b32_e32 v244, v192, v246, vcc
	v_sub_f32_e32 v192, v246, v244
	v_mul_f32_e32 v192, 0x3dd53b94, v192
	v_exp_f32_e32 v192, v192
	v_fmac_f32_e32 v178, 0xbdd53b94, v244
	v_mfma_f32_32x32x16_bf16 v[48:63], v[232:235], v[6:9], v[48:63]
	v_fmamk_f32 v214, v80, 0x3dd53b94, v178
	v_fmamk_f32 v215, v81, 0x3dd53b94, v178
	v_fmamk_f32 v212, v82, 0x3dd53b94, v178
	v_fmamk_f32 v213, v83, 0x3dd53b94, v178
	v_fmamk_f32 v210, v84, 0x3dd53b94, v178
	v_fmamk_f32 v211, v85, 0x3dd53b94, v178
	v_mfma_f32_32x32x16_bf16 v[48:63], v[236:239], v[10:13], v[48:63]
	v_fmamk_f32 v208, v86, 0x3dd53b94, v178
	v_fmamk_f32 v209, v87, 0x3dd53b94, v178
	v_fmamk_f32 v206, v88, 0x3dd53b94, v178
	v_fmamk_f32 v207, v89, 0x3dd53b94, v178
	v_fmamk_f32 v204, v90, 0x3dd53b94, v178
	v_fmamk_f32 v205, v91, 0x3dd53b94, v178
	v_mfma_f32_32x32x16_bf16 v[48:63], v[240:243], v[112:115], v[48:63]
	v_fmamk_f32 v202, v92, 0x3dd53b94, v178
	v_fmamk_f32 v203, v93, 0x3dd53b94, v178
	v_fmamk_f32 v200, v94, 0x3dd53b94, v178
	v_fmamk_f32 v201, v95, 0x3dd53b94, v178
	v_fmamk_f32 v96, v96, 0x3dd53b94, v178
	v_fmamk_f32 v97, v97, 0x3dd53b94, v178
	ds_read_b64_tr_b16 v[194:195], v217 offset:0x400
	ds_read_b64_tr_b16 v[196:197], v217 offset:0xc00
	ds_read_b64_tr_b16 v[232:233], v217 offset:0x1400
	ds_read_b64_tr_b16 v[234:235], v217 offset:0x1c00
	ds_read_b64_tr_b16 v[236:237], v217 offset:0x2400
	ds_read_b64_tr_b16 v[238:239], v217 offset:0x2c00
	ds_read_b64_tr_b16 v[240:241], v217 offset:0x3400
	ds_read_b64_tr_b16 v[242:243], v217 offset:0x3c00
	s_nop 0
	s_waitcnt lgkmcnt(0)
	s_nop 0
	v_mfma_f32_32x32x16_bf16 v[32:47], v[194:197], v[2:5], v[32:47]
	v_fmamk_f32 v98, v98, 0x3dd53b94, v178
	v_fmamk_f32 v99, v99, 0x3dd53b94, v178
	v_exp_f32_e32 v80, v96
	v_exp_f32_e32 v81, v97
	v_mfma_f32_32x32x16_bf16 v[32:47], v[232:235], v[6:9], v[32:47]
	v_fmamk_f32 v100, v100, 0x3dd53b94, v178
	v_fmamk_f32 v101, v101, 0x3dd53b94, v178
	v_exp_f32_e32 v82, v98
	v_exp_f32_e32 v83, v99
	v_mfma_f32_32x32x16_bf16 v[32:47], v[236:239], v[10:13], v[32:47]
	v_fmamk_f32 v102, v102, 0x3dd53b94, v178
	v_fmamk_f32 v103, v103, 0x3dd53b94, v178
	v_exp_f32_e32 v84, v100
	v_exp_f32_e32 v85, v101
	v_mfma_f32_32x32x16_bf16 v[32:47], v[240:243], v[112:115], v[32:47]
	v_fmamk_f32 v104, v104, 0x3dd53b94, v178
	v_fmamk_f32 v105, v105, 0x3dd53b94, v178
	v_exp_f32_e32 v86, v102
	v_exp_f32_e32 v87, v103
	ds_read_b64_tr_b16 v[194:195], v217 offset:0x600
	ds_read_b64_tr_b16 v[196:197], v217 offset:0xe00
	ds_read_b64_tr_b16 v[232:233], v217 offset:0x1600
	ds_read_b64_tr_b16 v[234:235], v217 offset:0x1e00
	ds_read_b64_tr_b16 v[236:237], v217 offset:0x2600
	ds_read_b64_tr_b16 v[238:239], v217 offset:0x2e00
	ds_read_b64_tr_b16 v[240:241], v217 offset:0x3600
	ds_read_b64_tr_b16 v[242:243], v217 offset:0x3e00
	s_nop 0
	s_waitcnt lgkmcnt(0)
	s_nop 0
	v_mfma_f32_32x32x16_bf16 v[16:31], v[194:197], v[2:5], v[16:31]
	v_fmamk_f32 v106, v106, 0x3dd53b94, v178
	v_fmamk_f32 v107, v107, 0x3dd53b94, v178
	v_exp_f32_e32 v88, v104
	v_exp_f32_e32 v89, v105
	v_mfma_f32_32x32x16_bf16 v[16:31], v[232:235], v[6:9], v[16:31]
	v_fmamk_f32 v108, v108, 0x3dd53b94, v178
	v_fmamk_f32 v109, v109, 0x3dd53b94, v178
	v_exp_f32_e32 v90, v106
	v_exp_f32_e32 v91, v107
	v_mfma_f32_32x32x16_bf16 v[16:31], v[236:239], v[10:13], v[16:31]
	v_fmamk_f32 v110, v110, 0x3dd53b94, v178
	v_fmamk_f32 v111, v111, 0x3dd53b94, v178
	v_exp_f32_e32 v92, v108
	v_exp_f32_e32 v93, v109
	v_mfma_f32_32x32x16_bf16 v[16:31], v[240:243], v[112:115], v[16:31]
	v_cmp_gt_f32_e32 vcc, 1.0, v192
	s_cbranch_vccz .LBB0_335
	v_pk_mul_f32 v[78:79], v[78:79], v[192:193] op_sel_hi:[1,0]
	v_pk_mul_f32 v[76:77], v[76:77], v[192:193] op_sel_hi:[1,0]
	v_pk_mul_f32 v[74:75], v[74:75], v[192:193] op_sel_hi:[1,0]
	v_pk_mul_f32 v[72:73], v[72:73], v[192:193] op_sel_hi:[1,0]
	v_pk_mul_f32 v[70:71], v[70:71], v[192:193] op_sel_hi:[1,0]
	v_pk_mul_f32 v[68:69], v[68:69], v[192:193] op_sel_hi:[1,0]
	v_pk_mul_f32 v[66:67], v[66:67], v[192:193] op_sel_hi:[1,0]
	v_pk_mul_f32 v[64:65], v[64:65], v[192:193] op_sel_hi:[1,0]
	v_pk_mul_f32 v[62:63], v[192:193], v[62:63] op_sel_hi:[0,1]
	v_pk_mul_f32 v[60:61], v[192:193], v[60:61] op_sel_hi:[0,1]
	v_pk_mul_f32 v[58:59], v[192:193], v[58:59] op_sel_hi:[0,1]
	v_pk_mul_f32 v[56:57], v[192:193], v[56:57] op_sel_hi:[0,1]
	v_pk_mul_f32 v[54:55], v[192:193], v[54:55] op_sel_hi:[0,1]
	v_pk_mul_f32 v[52:53], v[192:193], v[52:53] op_sel_hi:[0,1]
	v_pk_mul_f32 v[50:51], v[192:193], v[50:51] op_sel_hi:[0,1]
	v_pk_mul_f32 v[48:49], v[192:193], v[48:49] op_sel_hi:[0,1]
	v_pk_mul_f32 v[46:47], v[192:193], v[46:47] op_sel_hi:[0,1]
	v_pk_mul_f32 v[44:45], v[192:193], v[44:45] op_sel_hi:[0,1]
	v_pk_mul_f32 v[42:43], v[192:193], v[42:43] op_sel_hi:[0,1]
	v_pk_mul_f32 v[40:41], v[192:193], v[40:41] op_sel_hi:[0,1]
	v_pk_mul_f32 v[38:39], v[192:193], v[38:39] op_sel_hi:[0,1]
	v_pk_mul_f32 v[36:37], v[192:193], v[36:37] op_sel_hi:[0,1]
	v_pk_mul_f32 v[34:35], v[192:193], v[34:35] op_sel_hi:[0,1]
	v_pk_mul_f32 v[32:33], v[192:193], v[32:33] op_sel_hi:[0,1]
	v_pk_mul_f32 v[30:31], v[192:193], v[30:31] op_sel_hi:[0,1]
	v_pk_mul_f32 v[28:29], v[192:193], v[28:29] op_sel_hi:[0,1]
	v_pk_mul_f32 v[26:27], v[192:193], v[26:27] op_sel_hi:[0,1]
	v_pk_mul_f32 v[24:25], v[192:193], v[24:25] op_sel_hi:[0,1]
	v_pk_mul_f32 v[22:23], v[192:193], v[22:23] op_sel_hi:[0,1]
	v_pk_mul_f32 v[20:21], v[192:193], v[20:21] op_sel_hi:[0,1]
	v_pk_mul_f32 v[18:19], v[192:193], v[18:19] op_sel_hi:[0,1]
	v_pk_mul_f32 v[16:17], v[192:193], v[16:17] op_sel_hi:[0,1]
